# ssd_p1 B/X conv loops only: lanes remapped to 16 tokens x 4 channel groups per wave
# baseline (speedup 1.0000x reference)
; DI unsigned pk2(float lo, float hi) { f32x2 v = {lo, hi}; bf16v2 b = __builtin_convertvector(v, bf16v2); return __builtin_bit_cast(unsigned, b); }
; DI void conv8(const bf16_t* proj, int b, int t, int chx, const float* cw, const float* cbias, float (&o)[8]) {
;     const f32x4 b0 = *(const f32x4*)(cbias + chx), b1 = *(const f32x4*)(cbias + chx + 4);
;     float a[8] = {b0.x, b0.y, b0.z, b0.w, b1.x, b1.y, b1.z, b1.w};
; #pragma unroll
;     for (int k = 0; k < 4; ++k) { const int tt = t - 3 + k;
;         if (tt >= 0) { const u32x4 v = *(const u32x4*)(proj + (size_t)(b * T + tt) * NINP + C_XBC + chx);
; DI void ssd_p1_item(const Params& p, int L, int item, LAS unsigned char* lds, int tid) {
;     ...
;         acs[tid] = sc + ((w & 1) ? wtot[w - 1] : 0.f);
;     }
;     __syncthreads();
; #pragma unroll 1
;     for (int i = 0; i < 4; ++i) { const int u = tid + 512 * i, l = u & 127, ch = (u >> 7) * 8; float o[8];
;         conv8(proj, b, c * 128 + l, 512 + g * 128 + ch, cw, cb, o);
; #pragma unroll
;         for (int e = 0; e < 8; e += 2) { const unsigned pk = pk2(o[e], o[e + 1]);
;             BT[(ch + e) * 136 + l] = (bf16_t)(pk & 0xffffu); BT[(ch + e + 1) * 136 + l] = (bf16_t)(pk >> 16); } }
.LBB0_266:
	v_cmp_gt_u32_e32 vcc, 32, v6
	v_add_u32_e32 v25, 0x1a000, v5
	s_mov_b64 s[62:63], 0x1830
	v_cndmask_b32_e32 v2, v3, v2, vcc
	s_waitcnt lgkmcnt(0)
	v_add_f32_e32 v2, v2, v7
	ds_write_b32 v25, v2
	v_lshrrev_b32_e32 v46, 2, v27
	v_and_b32_e32 v47, 3, v27
	v_lshlrev_b32_e32 v47, 7, v47
	v_sub_u32_e32 v4, v4, v24
	v_add_u32_e32 v4, v4, v46
	v_add_u32_e32 v2, s56, v4
	v_mov_b64_e32 v[0:1], s[24:25]
	v_mad_i64_i32 v[2:3], s[100:101], v2, s96, v[0:1]
	v_lshl_add_u64 v[8:9], v[2:3], 0, s[62:63]
	v_add3_u32 v2, s56, -3, v4
	v_mov_b64_e32 v[0:1], s[24:25]
	v_mad_i64_i32 v[2:3], s[24:25], v2, s96, v[0:1]
	v_lshl_add_u64 v[10:11], v[2:3], 0, s[62:63]
	v_add3_u32 v2, s56, -2, v4
	s_xor_b64 s[18:19], s[8:9], -1
	v_mad_i64_i32 v[2:3], s[24:25], v2, s96, v[0:1]
	s_add_u32 s20, s10, s14
	v_lshl_add_u64 v[12:13], v[2:3], 0, s[62:63]
	v_add3_u32 v2, s56, -1, v4
	s_addc_u32 s21, s11, s15
	v_mad_i64_i32 v[0:1], s[24:25], v2, s96, v[0:1]
	s_add_u32 s22, s22, s16
	v_readlane_b32 s24, v255, 2
	s_addc_u32 s23, s23, s17
	v_cmp_lt_u32_e64 s[6:7], 2, v4
	v_cmp_lt_u32_e64 s[8:9], 1, v4
	s_mov_b32 s55, 0
	v_cmp_ne_u32_e64 s[10:11], 0, v4
	v_lshl_add_u64 v[14:15], v[0:1], 0, s[62:63]
	v_lshl_add_u32 v16, v46, 1, s24
	s_waitcnt lgkmcnt(0)
	s_barrier
	s_branch .LBB0_268

; DI float bflo(unsigned v) { return __uint_as_float(v << 16); }
; DI float bfhi(unsigned v) { return __uint_as_float(v & 0xffff0000u); }
; DI void conv8(const bf16_t* proj, int b, int t, int chx, const float* cw, const float* cbias, float (&o)[8]) {
;     const f32x4 b0 = *(const f32x4*)(cbias + chx), b1 = *(const f32x4*)(cbias + chx + 4);
;     float a[8] = {b0.x, b0.y, b0.z, b0.w, b1.x, b1.y, b1.z, b1.w};
; #pragma unroll
;     for (int k = 0; k < 4; ++k) { const int tt = t - 3 + k;
;         if (tt >= 0) { const u32x4 v = *(const u32x4*)(proj + (size_t)(b * T + tt) * NINP + C_XBC + chx);
;             const f32x4 w0 = *(const f32x4*)(cw + k * 1024 + chx), w1 = *(const f32x4*)(cw + k * 1024 + chx + 4);
;             a[0] += w0.x * bflo(v.x); a[1] += w0.y * bfhi(v.x); a[2] += w0.z * bflo(v.y); a[3] += w0.w * bfhi(v.y);
;             a[4] += w1.x * bflo(v.z); a[5] += w1.y * bfhi(v.z); a[6] += w1.z * bflo(v.w); a[7] += w1.w * bfhi(v.w); } }
.LBB0_268:
	v_add_u32_e32 v0, s55, v47
	v_ashrrev_i32_e32 v0, 4, v0
	v_and_b32_e32 v18, -8, v0
	v_ashrrev_i32_e32 v19, 31, v18
	v_lshl_add_u64 v[0:1], s[66:67], 0, v[18:19]
	v_lshlrev_b64 v[22:23], 2, v[0:1]
	v_lshl_add_u64 v[4:5], s[22:23], 0, v[22:23]
	global_load_dwordx4 v[0:3], v[4:5], off offset:2064
	s_nop 0
	global_load_dwordx4 v[4:7], v[4:5], off offset:2048
	v_add_u32_e32 v20, s51, v18
	v_ashrrev_i32_e32 v21, 31, v20
	v_lshl_add_u64 v[22:23], s[20:21], 0, v[22:23]
	s_and_saveexec_b64 s[24:25], s[6:7]
	s_cbranch_execz .LBB0_271
	v_lshl_add_u64 v[28:29], v[20:21], 1, v[10:11]
	global_load_dwordx4 v[28:31], v[28:29], off
	s_nop 0
	global_load_dwordx4 v[32:35], v[22:23], off offset:2064
	global_load_dwordx4 v[36:39], v[22:23], off offset:2048
	s_waitcnt vmcnt(2)
	v_lshlrev_b32_e32 v40, 16, v28
	v_and_b32_e32 v41, 0xffff0000, v28
	v_lshlrev_b32_e32 v28, 16, v29
	v_and_b32_e32 v29, 0xffff0000, v29
	s_waitcnt vmcnt(0)
	v_pk_fma_f32 v[6:7], v[38:39], v[28:29], v[6:7]
	v_lshlrev_b32_e32 v28, 16, v30
	v_and_b32_e32 v29, 0xffff0000, v30
	v_pk_fma_f32 v[0:1], v[32:33], v[28:29], v[0:1]
	v_lshlrev_b32_e32 v28, 16, v31
	v_and_b32_e32 v29, 0xffff0000, v31
	v_pk_fma_f32 v[4:5], v[36:37], v[40:41], v[4:5]
	v_pk_fma_f32 v[2:3], v[34:35], v[28:29], v[2:3]
	s_or_b64 exec, exec, s[24:25]
	v_lshl_add_u64 v[22:23], v[22:23], 0, s[34:35]
	s_and_saveexec_b64 s[24:25], s[8:9]
	s_cbranch_execnz .LBB0_272

; DI unsigned pk2(float lo, float hi) { f32x2 v = {lo, hi}; bf16v2 b = __builtin_convertvector(v, bf16v2); return __builtin_bit_cast(unsigned, b); }
; DI float bflo(unsigned v) { return __uint_as_float(v << 16); }
; DI float bfhi(unsigned v) { return __uint_as_float(v & 0xffff0000u); }
; DI float silu_f(float x) { return x * __builtin_amdgcn_rcpf(1.f + __expf(-x)); }
; DI void conv8(const bf16_t* proj, int b, int t, int chx, const float* cw, const float* cbias, float (&o)[8]) {
;     const f32x4 b0 = *(const f32x4*)(cbias + chx), b1 = *(const f32x4*)(cbias + chx + 4);
;     float a[8] = {b0.x, b0.y, b0.z, b0.w, b1.x, b1.y, b1.z, b1.w};
; #pragma unroll
;     for (int k = 0; k < 4; ++k) { const int tt = t - 3 + k;
;         if (tt >= 0) { const u32x4 v = *(const u32x4*)(proj + (size_t)(b * T + tt) * NINP + C_XBC + chx);
;             const f32x4 w0 = *(const f32x4*)(cw + k * 1024 + chx), w1 = *(const f32x4*)(cw + k * 1024 + chx + 4);
;             a[0] += w0.x * bflo(v.x); a[1] += w0.y * bfhi(v.x); a[2] += w0.z * bflo(v.y); a[3] += w0.w * bfhi(v.y);
;             a[4] += w1.x * bflo(v.z); a[5] += w1.y * bfhi(v.z); a[6] += w1.z * bflo(v.w); a[7] += w1.w * bfhi(v.w); } }
; #pragma unroll
;     for (int e = 0; e < 8; ++e) o[e] = silu_f(a[e]);
; DI void ssd_p1_item(const Params& p, int L, int item, LAS unsigned char* lds, int tid) {
;     ...
;     for (int i = 0; i < 8; ++i) { const int u = tid + 512 * i, l = u & 127, rest = u >> 7, hx = rest >> 3, ch = (rest & 7) * 8; float o[8];
;         conv8(proj, b, c * 128 + l, (g * 4 + hx) * 64 + ch, cw, cb, o);
;         const float wgt = __expf(acs[hx * 128 + 127] - acs[hx * 128 + l]) * dts[hx * 128 + l];
; #pragma unroll
;         for (int e = 0; e < 8; e += 2) { const unsigned pk = pk2(o[e] * wgt, o[e + 1] * wgt);
;             XT[(hx * 64 + ch + e) * 136 + l] = (bf16_t)(pk & 0xffffu); XT[(hx * 64 + ch + e + 1) * 136 + l] = (bf16_t)(pk >> 16); } }
.LBB0_274:
	v_lshl_add_u32 v16, v46, 1, 0
	s_mov_b32 s55, 0
	s_branch .LBB0_276
.LBB0_275:
	s_or_b64 exec, exec, s[24:25]
	v_lshl_add_u64 v[20:21], v[20:21], 1, v[8:9]
	global_load_dwordx4 v[28:31], v[20:21], off
	v_lshl_add_u64 v[32:33], v[18:19], 0, s[44:45]
	v_add_co_u32_e32 v18, vcc, 0x3000, v18
	v_lshlrev_b32_e32 v36, 9, v22
	s_nop 0
	v_addc_co_u32_e32 v19, vcc, 0, v19, vcc
	global_load_dwordx4 v[18:21], v[18:19], off
	s_nop 0
	global_load_dwordx4 v[32:35], v[32:33], off offset:16
	s_add_i32 s24, 0, 0x1a000
	v_add_u32_e32 v37, s24, v36
	v_lshl_or_b32 v36, v46, 2, v36
	v_add_u32_e32 v38, s24, v36
	ds_read_b32 v37, v37 offset:508
	ds_read_b32 v38, v38
	v_add_u32_e32 v36, 0, v36
	v_add_u32_e32 v36, 0x19800, v36
	ds_read_b32 v36, v36
	s_addk_i32 s55, 0x200
	s_waitcnt lgkmcnt(1)
	v_sub_f32_e32 v37, v37, v38
	v_mul_f32_e32 v37, 0x3fb8aa3b, v37
	v_exp_f32_e32 v37, v37
	s_cmpk_eq_i32 s55, 0x1000
	s_waitcnt lgkmcnt(0)
	v_mul_f32_e32 v36, v36, v37
	v_lshl_or_b32 v37, v22, 6, v23
	s_waitcnt vmcnt(2)
	v_lshlrev_b32_e32 v22, 16, v28
	v_and_b32_e32 v23, 0xffff0000, v28
	s_waitcnt vmcnt(1)
	v_pk_fma_f32 v[4:5], v[18:19], v[22:23], v[4:5]
	s_nop 0
	v_mul_f32_e32 v18, 0xbfb8aa3b, v4
	v_mul_f32_e32 v19, 0xbfb8aa3b, v5
	v_exp_f32_e32 v18, v18
	v_exp_f32_e32 v19, v19
	v_add_f32_e32 v18, 1.0, v18
	v_add_f32_e32 v19, 1.0, v19
	v_rcp_f32_e32 v18, v18
	v_rcp_f32_e32 v19, v19
	s_nop 0
	v_pk_mul_f32 v[4:5], v[4:5], v[18:19]
	s_nop 0
	v_pk_mul_f32 v[4:5], v[36:37], v[4:5] op_sel_hi:[0,1]
	v_cvt_pk_bf16_f32 v18, v4, v5
	v_mad_u64_u32 v[4:5], s[24:25], v37, s68, v[16:17]
	ds_write_b16 v4, v18
	ds_write_b16_d16_hi v4, v18 offset:272
	v_lshlrev_b32_e32 v18, 16, v29
	v_and_b32_e32 v19, 0xffff0000, v29
	v_pk_fma_f32 v[6:7], v[20:21], v[18:19], v[6:7]
	s_nop 0
	v_mul_f32_e32 v5, 0xbfb8aa3b, v6
	v_exp_f32_e32 v5, v5
	s_nop 0
	v_add_f32_e32 v5, 1.0, v5
	v_rcp_f32_e32 v18, v5
	v_mul_f32_e32 v5, 0xbfb8aa3b, v7
	v_exp_f32_e32 v5, v5
	s_nop 0
	v_add_f32_e32 v5, 1.0, v5
	v_rcp_f32_e32 v19, v5
	s_nop 0
	v_pk_mul_f32 v[6:7], v[6:7], v[18:19]
	s_nop 0
	v_pk_mul_f32 v[6:7], v[36:37], v[6:7] op_sel_hi:[0,1]
	v_cvt_pk_bf16_f32 v5, v6, v7
	v_lshlrev_b32_e32 v6, 16, v30
	v_and_b32_e32 v7, 0xffff0000, v30
	s_waitcnt vmcnt(0)
	v_pk_fma_f32 v[0:1], v[32:33], v[6:7], v[0:1]
	ds_write_b16 v4, v5 offset:544
	ds_write_b16_d16_hi v4, v5 offset:816
	v_mul_f32_e32 v5, 0xbfb8aa3b, v0
	v_exp_f32_e32 v5, v5
	s_nop 0
	v_add_f32_e32 v5, 1.0, v5
	v_rcp_f32_e32 v6, v5
	v_mul_f32_e32 v5, 0xbfb8aa3b, v1
	v_exp_f32_e32 v5, v5
	s_nop 0
	v_add_f32_e32 v5, 1.0, v5
	v_rcp_f32_e32 v7, v5
	s_nop 0
	v_pk_mul_f32 v[0:1], v[0:1], v[6:7]
	s_nop 0
	v_pk_mul_f32 v[0:1], v[36:37], v[0:1] op_sel_hi:[0,1]
	v_cvt_pk_bf16_f32 v0, v0, v1
	ds_write_b16 v4, v0 offset:1088
	ds_write_b16_d16_hi v4, v0 offset:1360
	v_lshlrev_b32_e32 v0, 16, v31
	v_and_b32_e32 v1, 0xffff0000, v31
	v_pk_fma_f32 v[0:1], v[34:35], v[0:1], v[2:3]
	s_nop 0
	v_mul_f32_e32 v2, 0xbfb8aa3b, v0
	v_mul_f32_e32 v3, 0xbfb8aa3b, v1
	v_exp_f32_e32 v2, v2
	v_exp_f32_e32 v3, v3
	v_add_f32_e32 v2, 1.0, v2
	v_add_f32_e32 v3, 1.0, v3
	v_rcp_f32_e32 v2, v2
	v_rcp_f32_e32 v3, v3
	s_nop 0
	v_pk_mul_f32 v[0:1], v[0:1], v[2:3]
	s_nop 0
	v_pk_mul_f32 v[0:1], v[36:37], v[0:1] op_sel_hi:[0,1]
	v_cvt_pk_bf16_f32 v0, v0, v1
	ds_write_b16 v4, v0 offset:1632
	ds_write_b16_d16_hi v4, v0 offset:1904
	s_cbranch_scc1 .LBB0_282
.LBB0_276:
	v_add_u32_e32 v0, s55, v47
	v_ashrrev_i32_e32 v22, 10, v0
	v_lshrrev_b32_e32 v0, 4, v0
	v_and_b32_e32 v23, 56, v0
	v_add_u32_e32 v0, s50, v22
	v_lshl_or_b32 v20, v0, 6, v23
	v_ashrrev_i32_e32 v21, 31, v20
	v_lshlrev_b64 v[18:19], 2, v[20:21]
	v_lshl_add_u64 v[4:5], s[22:23], 0, v[18:19]
	global_load_dwordx4 v[0:3], v[4:5], off offset:16
	s_nop 0
	global_load_dwordx4 v[4:7], v[4:5], off
	v_lshl_add_u64 v[18:19], s[20:21], 0, v[18:19]
	s_and_saveexec_b64 s[24:25], s[6:7]
	s_cbranch_execz .LBB0_279
	v_lshl_add_u64 v[28:29], v[20:21], 1, v[10:11]
	global_load_dwordx4 v[28:31], v[28:29], off
	s_nop 0
	global_load_dwordx4 v[32:35], v[18:19], off offset:16
	global_load_dwordx4 v[36:39], v[18:19], off
	s_waitcnt vmcnt(2)
	v_lshlrev_b32_e32 v40, 16, v28
	v_and_b32_e32 v41, 0xffff0000, v28
	v_lshlrev_b32_e32 v28, 16, v29
	v_and_b32_e32 v29, 0xffff0000, v29
	s_waitcnt vmcnt(0)
	v_pk_fma_f32 v[6:7], v[38:39], v[28:29], v[6:7]
	v_lshlrev_b32_e32 v28, 16, v30
	v_and_b32_e32 v29, 0xffff0000, v30
	v_pk_fma_f32 v[0:1], v[32:33], v[28:29], v[0:1]
	v_lshlrev_b32_e32 v28, 16, v31
	v_and_b32_e32 v29, 0xffff0000, v31
	v_pk_fma_f32 v[4:5], v[36:37], v[40:41], v[4:5]
	v_pk_fma_f32 v[2:3], v[34:35], v[28:29], v[2:3]
	s_or_b64 exec, exec, s[24:25]
	s_and_saveexec_b64 s[24:25], s[8:9]
	s_cbranch_execnz .LBB0_280
